# GEMM tile start: removed the vmcnt(0) drain before accumulator zeroing (epilogue stores drain under the next tile's first K-steps; loop vmcnt(6) protocol unchanged)
# speedup vs baseline: 1.0053x; 1.0053x over previous
; __device__ __forceinline__ void gemm_phase(LAS unsigned char* lds, const Gemm g, const StaticOrder& S, const Epi& E) {
;     ...
; #pragma unroll
;         for (int a = 0; a < 2; ++a)
; #pragma unroll
;             for (int b = 0; b < 2; ++b)
; #pragma unroll
;                 for (int m = 0; m < 4; ++m)
; #pragma unroll
;                     for (int n = 0; n < 2; ++n) acc[a][b][m][n] = (f32x4){0.f, 0.f, 0.f, 0.f};
;         cur = nxt; cA = nA; cB = nB; ++ui;
.LBB0_761:
	s_add_u32 s0, s34, 0x80
	s_addc_u32 s1, s35, 0
	s_add_u32 s27, s36, 0x100
	v_mov_b32_e32 v0, 0
	s_addc_u32 s33, s37, 0
	s_mov_b32 s34, 0
	v_mov_b32_e32 v1, v0
	v_mov_b32_e32 v2, v0
	v_mov_b32_e32 v3, v0
	v_mov_b32_e32 v4, v0
	v_mov_b32_e32 v5, v0
	v_mov_b32_e32 v6, v0
	v_mov_b32_e32 v7, v0
	v_mov_b32_e32 v16, v0
	v_mov_b32_e32 v17, v0
	v_mov_b32_e32 v18, v0
	v_mov_b32_e32 v19, v0
	v_mov_b32_e32 v20, v0
	v_mov_b32_e32 v21, v0
	v_mov_b32_e32 v22, v0
	v_mov_b32_e32 v23, v0
	v_mov_b32_e32 v32, v0
	v_mov_b32_e32 v33, v0
	v_mov_b32_e32 v34, v0
	v_mov_b32_e32 v35, v0
	v_mov_b32_e32 v36, v0
	v_mov_b32_e32 v37, v0
	v_mov_b32_e32 v38, v0
	v_mov_b32_e32 v39, v0
	v_mov_b32_e32 v48, v0
	v_mov_b32_e32 v49, v0
	v_mov_b32_e32 v50, v0
	v_mov_b32_e32 v51, v0
	v_mov_b32_e32 v52, v0
	v_mov_b32_e32 v53, v0
	v_mov_b32_e32 v54, v0
	v_mov_b32_e32 v55, v0
	v_mov_b32_e32 v8, v0
	v_mov_b32_e32 v9, v0
	v_mov_b32_e32 v10, v0
	v_mov_b32_e32 v11, v0
	v_mov_b32_e32 v12, v0
	v_mov_b32_e32 v13, v0
	v_mov_b32_e32 v14, v0
	v_mov_b32_e32 v15, v0
	v_mov_b32_e32 v24, v0
	v_mov_b32_e32 v25, v0
	v_mov_b32_e32 v26, v0
	v_mov_b32_e32 v27, v0
	v_mov_b32_e32 v28, v0
	v_mov_b32_e32 v29, v0
	v_mov_b32_e32 v30, v0
	v_mov_b32_e32 v31, v0
	v_mov_b32_e32 v40, v0
	v_mov_b32_e32 v41, v0
	v_mov_b32_e32 v42, v0
	v_mov_b32_e32 v43, v0
	v_mov_b32_e32 v44, v0
	v_mov_b32_e32 v45, v0
	v_mov_b32_e32 v46, v0
	v_mov_b32_e32 v47, v0
	v_mov_b32_e32 v56, v0
	v_mov_b32_e32 v57, v0
	v_mov_b32_e32 v58, v0
	v_mov_b32_e32 v59, v0
	v_mov_b32_e32 v60, v0
	v_mov_b32_e32 v61, v0
	v_mov_b32_e32 v62, v0
	v_mov_b32_e32 v63, v0
	v_mov_b32_e32 v64, v0
	v_mov_b32_e32 v65, v0
	v_mov_b32_e32 v66, v0
	v_mov_b32_e32 v67, v0
	v_mov_b32_e32 v68, v0
	v_mov_b32_e32 v69, v0
	v_mov_b32_e32 v70, v0
	v_mov_b32_e32 v71, v0
	v_mov_b32_e32 v80, v0
	v_mov_b32_e32 v81, v0
	v_mov_b32_e32 v82, v0
	v_mov_b32_e32 v83, v0
	v_mov_b32_e32 v84, v0
	v_mov_b32_e32 v85, v0
	v_mov_b32_e32 v86, v0
	v_mov_b32_e32 v87, v0
	v_mov_b32_e32 v96, v0
	v_mov_b32_e32 v97, v0
	v_mov_b32_e32 v98, v0
	v_mov_b32_e32 v99, v0
	v_mov_b32_e32 v100, v0
	v_mov_b32_e32 v101, v0
	v_mov_b32_e32 v102, v0
	v_mov_b32_e32 v103, v0
	v_mov_b32_e32 v112, v0
	v_mov_b32_e32 v113, v0
	v_mov_b32_e32 v114, v0
	v_mov_b32_e32 v115, v0
	v_mov_b32_e32 v116, v0
	v_mov_b32_e32 v117, v0
	v_mov_b32_e32 v118, v0
	v_mov_b32_e32 v119, v0
	v_mov_b32_e32 v72, v0
	v_mov_b32_e32 v73, v0
	v_mov_b32_e32 v74, v0
	v_mov_b32_e32 v75, v0
	v_mov_b32_e32 v76, v0
	v_mov_b32_e32 v77, v0
	v_mov_b32_e32 v78, v0
	v_mov_b32_e32 v79, v0
	v_mov_b32_e32 v88, v0
	v_mov_b32_e32 v89, v0
	v_mov_b32_e32 v90, v0
	v_mov_b32_e32 v91, v0
	v_mov_b32_e32 v92, v0
	v_mov_b32_e32 v93, v0
	v_mov_b32_e32 v94, v0
	v_mov_b32_e32 v95, v0
	v_mov_b32_e32 v104, v0
	v_mov_b32_e32 v105, v0
	v_mov_b32_e32 v106, v0
	v_mov_b32_e32 v107, v0
	v_mov_b32_e32 v108, v0
	v_mov_b32_e32 v109, v0
	v_mov_b32_e32 v110, v0
	v_mov_b32_e32 v111, v0
	v_mov_b32_e32 v120, v0
	v_mov_b32_e32 v121, v0
	v_mov_b32_e32 v122, v0
	v_mov_b32_e32 v123, v0
	v_mov_b32_e32 v124, v0
	v_mov_b32_e32 v125, v0
	v_mov_b32_e32 v126, v0
	v_mov_b32_e32 v127, v0
	v_add_u32_e32 v224, 0x10000, v238
	v_add_u32_e32 v225, 0x14000, v238
	v_add_u32_e32 v241, 0x18000, v238
	v_add_u32_e32 v248, 0x1c000, v238
	s_cmpk_gt_u32 s57, 0xff
	s_cbranch_scc1 .Lprio_skip
	s_setprio 1
